# split barrier: XCD leader goes on right after its cross-XCD arrival (no wait for the atomic's ack), non-leader does not wait for the precautionary invalidate
# speedup vs baseline: 1.0004x; 1.0004x over previous
; __device__ __forceinline__ unsigned xb_ld(unsigned* p)              { return __hip_atomic_load(p, __ATOMIC_RELAXED, __HIP_MEMORY_SCOPE_AGENT); }
; __device__ __forceinline__ unsigned xb_add(unsigned* p, unsigned v) { return __hip_atomic_fetch_add(p, v, __ATOMIC_RELAXED, __HIP_MEMORY_SCOPE_AGENT); }
; #define XB_SPIN(cond, bar) do { unsigned _sp = 0; while (cond) { __builtin_amdgcn_s_sleep(1); \
;     if ((++_sp & 255u) == 0u) { if (xb_ld(&(bar)[XB_TMO])) break; if (_sp > XB_SPIN_CAP) { atomicAdd(&(bar)[XB_TMO], 1u); break; } } } } while (0)
; __device__ __forceinline__ void xcd_barrier(const XcdBarrier& b) {
;     ...
;         const unsigned old = xb_add(&bar[XB_XSUB(b.x)], 1u);
;         const unsigned gen = old / nloc;
;         if (old + 1u == (gen + 1u) * nloc) {
;             __builtin_amdgcn_fence(__ATOMIC_RELEASE, "agent");
;             asm volatile("s_waitcnt vmcnt(0)" ::: "memory");
;             const unsigned og = xb_add(&bar[XB_TOP], 1u);
;             const unsigned tg = og / nx;
;             if (og + 1u == (tg + 1u) * nx) xb_add(&bar[XB_TOPGEN], 1u);
;             else XB_SPIN(xb_ld(&bar[XB_TOPGEN]) == tg, bar);
;             __builtin_amdgcn_fence(__ATOMIC_ACQUIRE, "agent");
;             xb_add(&bar[XB_XGEN(b.x)], 1u);
;             asm volatile("s_waitcnt vmcnt(0)" ::: "memory");
;         } else {
;             XB_SPIN(xb_ld(&bar[XB_XGEN(b.x)]) == gen, bar);
;             __builtin_amdgcn_fence(__ATOMIC_ACQUIRE, "agent");
;             asm volatile("s_waitcnt vmcnt(0)" ::: "memory");
;         }
.LBB0_44:
	s_or_b64 exec, exec, s[10:11]
.LBB0_45:
	s_andn2_saveexec_b64 s[8:9], s[8:9]
	s_cbranch_execz .LBB0_65
	s_mov_b64 s[8:9], exec
	s_waitcnt lgkmcnt(0)
	s_waitcnt vmcnt(0)
	v_mbcnt_lo_u32_b32 v2, s8, 0
	v_mbcnt_hi_u32_b32 v2, s9, v2
	v_cmp_eq_u32_e32 vcc, 0, v2
	s_and_saveexec_b64 s[10:11], vcc
	s_cbranch_execz .LBB0_48
	s_bcnt1_i32_b64 s8, s[8:9]
	v_mov_b32_e32 v3, 0x7000
	v_mov_b32_e32 v4, s8
	global_atomic_add v3, v4, s[60:61] offset:1024
.LBB0_48:
	s_or_b64 exec, exec, s[10:11]
	buffer_inv sc1
	s_branch .LBB0_65
	v_cvt_f32_u32_e32 v4, v1
	s_waitcnt vmcnt(0)
	v_readfirstlane_b32 s8, v3
	buffer_inv sc1
	s_add_u32 s10, s60, 0x7400
	s_addc_u32 s11, s61, 0
	v_rcp_iflag_f32_e32 v4, v4
	v_add_u32_e32 v2, s8, v2
	v_add_u32_e32 v5, 1, v2
	s_mov_b64 s[12:13], 0
	v_mul_f32_e32 v3, 0x4f7ffffe, v4
	v_cvt_u32_f32_e32 v3, v3
	v_sub_u32_e32 v4, 0, v1
	v_mul_lo_u32 v4, v4, v3
	v_mul_hi_u32 v4, v3, v4
	v_add_u32_e32 v3, v3, v4
	v_mul_hi_u32 v3, v2, v3
	v_mul_lo_u32 v4, v3, v1
	v_sub_u32_e32 v2, v2, v4
	v_add_u32_e32 v6, 1, v3
	v_cmp_ge_u32_e32 vcc, v2, v1
	v_sub_u32_e32 v4, v2, v1
	s_nop 0
	v_cndmask_b32_e32 v3, v3, v6, vcc
	v_cndmask_b32_e32 v2, v2, v4, vcc
	v_add_u32_e32 v4, 1, v3
	v_cmp_ge_u32_e32 vcc, v2, v1
	s_nop 1
	v_cndmask_b32_e32 v4, v3, v4, vcc
	v_mul_lo_u32 v2, v1, v4
	v_add_u32_e32 v1, v2, v1
	s_mov_b64 vcc, 0
	v_mov_b64_e32 v[2:3], s[10:11]
	s_and_saveexec_b64 s[8:9], vcc
	s_cbranch_execz .LBB0_60
	v_mov_b32_e32 v4, v1
	v_mov_b32_e32 v1, 0
	global_load_dword v2, v1, s[10:11] sc1
	s_mov_b64 s[18:19], 0
	s_waitcnt vmcnt(0)
	v_cmp_lt_u32_e32 vcc, v2, v4
	s_and_saveexec_b64 s[16:17], vcc
	s_cbranch_execz .LBB0_59
	s_add_u32 s12, s60, 0x4200
	s_addc_u32 s13, s61, 0
	s_mov_b32 s14, 1
	s_branch .LBB0_52
